# stack of individually neutral edits: deferred attention->RNN barrier wait, rope-table load hoist, SGPR-base stores (output GEMM, XR/GR tiles), no L1 invalidate in LN exchange, no L2 write-back after a
# speedup vs baseline: 1.0034x; 1.0011x over previous
;     __device__ __forceinline__ void operator()(const pg8::f32x4 (&acc)[2][2][4][2], const pg8::Unit& u, int wr, int wc, int fr_, int fq_) const {
;     ...
;             for (int ai = 0; ai < 2; ++ai) {
;                 u32x4 rc[4][2];
; #pragma unroll
;                 for (int m = 0; m < 4; ++m) { const int pos = (row0 + ai * HALF + m * 16) & (SEQ - 1);
;                     const u32x4* rp = rope + ((size_t)pos * 64 + dlo) / 4;
;                     rc[m][0] = rp[0]; rc[m][1] = rp[1]; }
; #pragma unroll
;                 for (int m = 0; m < 4; ++m) {
;                     const int row = row0 + ai * HALF + m * 16;
;                     const u32x4 ca = rc[m][0], cb = rc[m][1];
;                     const f32x4 t1a = acc[ai][0][m][0] * ascale + bv[0][0], t1b = acc[ai][0][m][1] * ascale + bv[0][1];
;                     const f32x4 t2a = acc[ai][1][m][0] * ascale + bv[1][0], t2b = acc[ai][1][m][1] * ascale + bv[1][1];
.LBB0_424:
	s_and_b64 vcc, exec, s[64:65]
	s_cbranch_vccz .LBB0_440
	v_mov_b64_e32 v[198:199], v[178:179]
	v_add_u32_e32 v178, s48, v162
	v_lshlrev_b32_e32 v188, 6, v174
	v_ashrrev_i32_e32 v179, 31, v178
	v_and_b32_e32 v172, 0xfffc0, v188
	v_lshl_add_u64 v[144:145], v[172:173], 0, v[178:179]
	v_lshl_add_u64 v[144:145], v[144:145], 2, s[46:47]
	global_load_dwordx4 v[168:171], v[144:145], off offset:16
	global_load_dwordx4 v[190:193], v[144:145], off
	v_add_u32_e32 v144, 0x400, v188
	v_and_b32_e32 v172, 0xfffc0, v144
	v_lshl_add_u64 v[144:145], v[172:173], 0, v[178:179]
	v_lshl_add_u64 v[144:145], v[144:145], 2, s[46:47]
	global_load_dwordx4 v[160:163], v[144:145], off offset:16
	global_load_dwordx4 v[164:167], v[144:145], off
	v_add_u32_e32 v144, 0x800, v188
	v_and_b32_e32 v172, 0xfffc0, v144
	v_lshl_add_u64 v[144:145], v[172:173], 0, v[178:179]
	v_lshl_add_u64 v[144:145], v[144:145], 2, s[46:47]
	global_load_dwordx4 v[152:155], v[144:145], off offset:16
	global_load_dwordx4 v[156:159], v[144:145], off
	v_add_u32_e32 v144, 0xc00, v188
	v_and_b32_e32 v172, 0xfffc0, v144
	v_lshl_add_u64 v[144:145], v[172:173], 0, v[178:179]
	v_lshl_add_u64 v[148:149], v[144:145], 2, s[46:47]
	global_load_dwordx4 v[144:147], v[148:149], off offset:16
	s_nop 0
	global_load_dwordx4 v[148:151], v[148:149], off
	v_mov_b32_e32 v233, 0
	v_add_u32_e32 v232, 0x2000, v188
	v_and_b32_e32 v232, 0xfffc0, v232
	v_lshl_add_u64 v[234:235], v[232:233], 0, v[178:179]
	v_lshl_add_u64 v[234:235], v[234:235], 2, s[46:47]
	global_load_dwordx4 v[200:203], v[234:235], off offset:16
	global_load_dwordx4 v[204:207], v[234:235], off
	v_add_u32_e32 v232, 0x2400, v188
	v_and_b32_e32 v232, 0xfffc0, v232
	v_lshl_add_u64 v[234:235], v[232:233], 0, v[178:179]
	v_lshl_add_u64 v[234:235], v[234:235], 2, s[46:47]
	global_load_dwordx4 v[208:211], v[234:235], off offset:16
	global_load_dwordx4 v[212:215], v[234:235], off
	v_add_u32_e32 v232, 0x2800, v188
	v_and_b32_e32 v232, 0xfffc0, v232
	v_lshl_add_u64 v[234:235], v[232:233], 0, v[178:179]
	v_lshl_add_u64 v[234:235], v[234:235], 2, s[46:47]
	global_load_dwordx4 v[216:219], v[234:235], off offset:16
	global_load_dwordx4 v[220:223], v[234:235], off
	v_add_u32_e32 v232, 0x2c00, v188
	v_and_b32_e32 v232, 0xfffc0, v232
	v_lshl_add_u64 v[234:235], v[232:233], 0, v[178:179]
	v_lshl_add_u64 v[234:235], v[234:235], 2, s[46:47]
	global_load_dwordx4 v[224:227], v[234:235], off offset:16
	global_load_dwordx4 v[228:231], v[234:235], off
	s_cmp_lt_u32 s8, 18
	s_waitcnt vmcnt(16)
	v_pk_fma_f32 v[132:133], v[132:133], s[56:57], v[120:121] op_sel_hi:[1,0,1]
	v_pk_fma_f32 v[194:195], v[130:131], s[56:57], v[114:115] op_sel_hi:[1,0,1]
	v_pk_fma_f32 v[130:131], v[128:129], s[56:57], v[112:113] op_sel_hi:[1,0,1]
	s_cselect_b64 s[64:65], -1, 0
	s_lshl_b32 s2, s8, 1
	v_pk_fma_f32 v[140:141], v[140:141], s[56:57], v[124:125] op_sel_hi:[1,0,1]
	s_add_i32 s2, s41, s2
	s_and_b64 s[6:7], s[64:65], exec
	v_pk_fma_f32 v[134:135], v[134:135], s[56:57], v[122:123] op_sel_hi:[1,0,1]
	s_mov_b32 s6, 0xe000000
	v_pk_fma_f32 v[142:143], v[142:143], s[56:57], v[126:127] op_sel_hi:[1,0,1]
	s_cselect_b32 s6, s6, 0x12000000
	s_cselect_b32 s2, s2, s40
	s_add_u32 s6, s10, s6
	s_addc_u32 s7, s11, 0
	s_lshl_b32 s2, s2, 8
	v_pk_fma_f32 v[136:137], v[136:137], s[56:57], v[116:117] op_sel_hi:[1,0,1]
	s_add_u32 s6, s6, s2
	s_addc_u32 s7, s7, 0
	v_pk_fma_f32 v[138:139], v[138:139], s[56:57], v[118:119] op_sel_hi:[1,0,1]
	v_lshl_add_u64 v[176:177], v[178:179], 1, s[6:7]
	s_and_b64 s[6:7], s[64:65], exec
	v_ashrrev_i32_e32 v175, 31, v174
	s_cselect_b32 s8, 10, 8
	v_pk_fma_f32 v[100:101], v[100:101], s[56:57], v[120:121] op_sel_hi:[1,0,1]
	v_pk_fma_f32 v[108:109], v[108:109], s[56:57], v[124:125] op_sel_hi:[1,0,1]
	v_pk_fma_f32 v[102:103], v[102:103], s[56:57], v[122:123] op_sel_hi:[1,0,1]
	v_pk_fma_f32 v[110:111], v[110:111], s[56:57], v[126:127] op_sel_hi:[1,0,1]
	v_pk_fma_f32 v[104:105], v[104:105], s[56:57], v[116:117] op_sel_hi:[1,0,1]
	v_pk_fma_f32 v[106:107], v[106:107], s[56:57], v[118:119] op_sel_hi:[1,0,1]
	v_pk_fma_f32 v[84:85], v[84:85], s[56:57], v[120:121] op_sel_hi:[1,0,1]
	v_pk_fma_f32 v[92:93], v[92:93], s[56:57], v[124:125] op_sel_hi:[1,0,1]
	v_pk_fma_f32 v[86:87], v[86:87], s[56:57], v[122:123] op_sel_hi:[1,0,1]
	v_pk_fma_f32 v[94:95], v[94:95], s[56:57], v[126:127] op_sel_hi:[1,0,1]
	v_pk_fma_f32 v[88:89], v[88:89], s[56:57], v[116:117] op_sel_hi:[1,0,1]
	v_pk_fma_f32 v[90:91], v[90:91], s[56:57], v[118:119] op_sel_hi:[1,0,1]
	v_pk_fma_f32 v[68:69], v[68:69], s[56:57], v[120:121] op_sel_hi:[1,0,1]
	v_pk_fma_f32 v[76:77], v[76:77], s[56:57], v[124:125] op_sel_hi:[1,0,1]
	v_pk_fma_f32 v[70:71], v[70:71], s[56:57], v[122:123] op_sel_hi:[1,0,1]
	v_pk_fma_f32 v[78:79], v[78:79], s[56:57], v[126:127] op_sel_hi:[1,0,1]
	v_pk_fma_f32 v[72:73], v[72:73], s[56:57], v[116:117] op_sel_hi:[1,0,1]
	v_pk_fma_f32 v[74:75], v[74:75], s[56:57], v[118:119] op_sel_hi:[1,0,1]
	v_pk_fma_f32 v[52:53], v[52:53], s[56:57], v[120:121] op_sel_hi:[1,0,1]
	v_pk_fma_f32 v[60:61], v[60:61], s[56:57], v[124:125] op_sel_hi:[1,0,1]
	v_pk_fma_f32 v[54:55], v[54:55], s[56:57], v[122:123] op_sel_hi:[1,0,1]
	v_pk_fma_f32 v[62:63], v[62:63], s[56:57], v[126:127] op_sel_hi:[1,0,1]
	v_pk_fma_f32 v[56:57], v[56:57], s[56:57], v[116:117] op_sel_hi:[1,0,1]
	v_pk_fma_f32 v[58:59], v[58:59], s[56:57], v[118:119] op_sel_hi:[1,0,1]
	v_pk_fma_f32 v[36:37], v[36:37], s[56:57], v[120:121] op_sel_hi:[1,0,1]
	v_pk_fma_f32 v[44:45], v[44:45], s[56:57], v[124:125] op_sel_hi:[1,0,1]
	v_pk_fma_f32 v[38:39], v[38:39], s[56:57], v[122:123] op_sel_hi:[1,0,1]
	v_pk_fma_f32 v[46:47], v[46:47], s[56:57], v[126:127] op_sel_hi:[1,0,1]
	v_pk_fma_f32 v[40:41], v[40:41], s[56:57], v[116:117] op_sel_hi:[1,0,1]
	v_pk_fma_f32 v[42:43], v[42:43], s[56:57], v[118:119] op_sel_hi:[1,0,1]
	v_pk_fma_f32 v[20:21], v[20:21], s[56:57], v[120:121] op_sel_hi:[1,0,1]
	v_pk_fma_f32 v[28:29], v[28:29], s[56:57], v[124:125] op_sel_hi:[1,0,1]
	v_pk_fma_f32 v[22:23], v[22:23], s[56:57], v[122:123] op_sel_hi:[1,0,1]
	v_pk_fma_f32 v[30:31], v[30:31], s[56:57], v[126:127] op_sel_hi:[1,0,1]
	v_pk_fma_f32 v[24:25], v[24:25], s[56:57], v[116:117] op_sel_hi:[1,0,1]
	v_pk_fma_f32 v[26:27], v[26:27], s[56:57], v[118:119] op_sel_hi:[1,0,1]
	v_pk_fma_f32 v[4:5], v[4:5], s[56:57], v[120:121] op_sel_hi:[1,0,1]
	v_pk_fma_f32 v[12:13], v[12:13], s[56:57], v[124:125] op_sel_hi:[1,0,1]
	v_pk_fma_f32 v[6:7], v[6:7], s[56:57], v[122:123] op_sel_hi:[1,0,1]
	s_waitcnt vmcnt(14)
;     __device__ __forceinline__ void operator()(const pg8::f32x4 (&acc)[2][2][4][2], const pg8::Unit& u, int wr, int wc, int fr_, int fq_) const {
;     ...
;                 for (int m = 0; m < 4; ++m) {
;                     const int row = row0 + ai * HALF + m * 16;
;                     const u32x4 ca = rc[m][0], cb = rc[m][1];
;                     const f32x4 t1a = acc[ai][0][m][0] * ascale + bv[0][0], t1b = acc[ai][0][m][1] * ascale + bv[0][1];
;                     const f32x4 t2a = acc[ai][1][m][0] * ascale + bv[1][0], t2b = acc[ai][1][m][1] * ascale + bv[1][1];
;                     typedef float f2r __attribute__((ext_vector_type(2)));
;                     u32x4 w1, w2;
;     ...
;                     ROT2(t1a, t2a, ca, 0, w1.x, w2.x) ROT2(t1a, t2a, ca, 1, w1.y, w2.y) ROT2(t1b, t2b, cb, 0, w1.z, w2.z) ROT2(t1b, t2b, cb, 1, w1.w, w2.w)
;     ...
;                     bf16_t* rowp = dst + (size_t)row * pitch + head * HD + dlo;
;                     __builtin_nontemporal_store(w1, (u32x4*)(rowp)); __builtin_nontemporal_store(w2, (u32x4*)(rowp + 64));
	v_lshlrev_b32_e32 v128, 16, v190
	v_lshlrev_b32_e32 v129, 16, v191
	v_and_b32_e32 v190, 0xffff0000, v190
	v_and_b32_e32 v191, 0xffff0000, v191
	v_pk_mul_f32 v[196:197], v[132:133], v[190:191]
	v_pk_fma_f32 v[14:15], v[14:15], s[56:57], v[126:127] op_sel_hi:[1,0,1]
	v_pk_fma_f32 v[196:197], v[140:141], v[128:129], v[196:197] neg_lo:[0,0,1] neg_hi:[0,0,1]
	v_pk_mul_f32 v[128:129], v[132:133], v[128:129]
	v_cvt_pk_bf16_f32 v132, v196, v197
	v_pk_fma_f32 v[8:9], v[8:9], s[56:57], v[116:117] op_sel_hi:[1,0,1]
	v_pk_fma_f32 v[128:129], v[140:141], v[190:191], v[128:129]
	v_lshlrev_b32_e32 v140, 16, v192
	v_lshlrev_b32_e32 v141, 16, v193
	v_and_b32_e32 v190, 0xffff0000, v192
	v_and_b32_e32 v191, 0xffff0000, v193
	v_pk_mul_f32 v[192:193], v[134:135], v[190:191]
	v_pk_mul_f32 v[134:135], v[134:135], v[140:141]
	v_cvt_pk_bf16_f32 v128, v128, v129
	v_pk_fma_f32 v[192:193], v[142:143], v[140:141], v[192:193] neg_lo:[0,0,1] neg_hi:[0,0,1]
	v_pk_fma_f32 v[134:135], v[142:143], v[190:191], v[134:135]
	v_cvt_pk_bf16_f32 v133, v192, v193
	v_and_b32_e32 v140, 0xffff0000, v168
	v_cvt_pk_bf16_f32 v129, v134, v135
	v_lshlrev_b32_e32 v134, 16, v168
	v_lshlrev_b32_e32 v135, 16, v169
	v_and_b32_e32 v141, 0xffff0000, v169
	v_pk_mul_f32 v[142:143], v[130:131], v[140:141]
	v_pk_mul_f32 v[130:131], v[130:131], v[134:135]
	v_pk_fma_f32 v[142:143], v[136:137], v[134:135], v[142:143] neg_lo:[0,0,1] neg_hi:[0,0,1]
	v_pk_fma_f32 v[130:131], v[136:137], v[140:141], v[130:131]
	v_and_b32_e32 v140, 0xffff0000, v170
	v_and_b32_e32 v141, 0xffff0000, v171
	v_cvt_pk_bf16_f32 v134, v142, v143
	v_lshlrev_b32_e32 v136, 16, v170
	v_lshlrev_b32_e32 v137, 16, v171
	v_pk_mul_f32 v[142:143], v[194:195], v[140:141]
	v_cvt_pk_bf16_f32 v130, v130, v131
	v_pk_fma_f32 v[10:11], v[10:11], s[56:57], v[118:119] op_sel_hi:[1,0,1]
	v_pk_fma_f32 v[142:143], v[138:139], v[136:137], v[142:143] neg_lo:[0,0,1] neg_hi:[0,0,1]
	v_pk_mul_f32 v[136:137], v[194:195], v[136:137]
	v_cvt_pk_bf16_f32 v135, v142, v143
	s_nop 0
	v_pk_fma_f32 v[136:137], v[138:139], v[140:141], v[136:137]
	s_nop 0
	v_cvt_pk_bf16_f32 v131, v136, v137
	v_lshlrev_b64 v[136:137], s8, v[174:175]
	v_lshl_add_u64 v[136:137], v[136:137], 1, v[176:177]
	global_store_dwordx4 v[136:137], v[132:135], off
	global_store_dwordx4 v[136:137], v[128:131], off offset:128
	s_waitcnt vmcnt(14)
	v_and_b32_e32 v132, 0xffff0000, v164
	v_and_b32_e32 v133, 0xffff0000, v165
	v_pk_fma_f32 v[130:131], v[98:99], s[56:57], v[114:115] op_sel_hi:[1,0,1]
	v_pk_fma_f32 v[98:99], v[96:97], s[56:57], v[112:113] op_sel_hi:[1,0,1]
	v_lshlrev_b32_e32 v96, 16, v164
	v_lshlrev_b32_e32 v97, 16, v165
	v_pk_mul_f32 v[134:135], v[100:101], v[132:133]
	v_add_u32_e32 v128, 16, v174
	v_pk_fma_f32 v[134:135], v[108:109], v[96:97], v[134:135] neg_lo:[0,0,1] neg_hi:[0,0,1]
	v_pk_mul_f32 v[96:97], v[100:101], v[96:97]
	v_ashrrev_i32_e32 v129, 31, v128
	v_pk_fma_f32 v[100:101], v[108:109], v[132:133], v[96:97]
	v_lshlrev_b32_e32 v108, 16, v166
	v_lshlrev_b32_e32 v109, 16, v167
	v_and_b32_e32 v132, 0xffff0000, v166
	v_and_b32_e32 v133, 0xffff0000, v167
	v_cvt_pk_bf16_f32 v96, v134, v135
	v_pk_mul_f32 v[134:135], v[102:103], v[132:133]
	v_pk_mul_f32 v[102:103], v[102:103], v[108:109]
	v_cvt_pk_bf16_f32 v100, v100, v101
	v_pk_fma_f32 v[134:135], v[110:111], v[108:109], v[134:135] neg_lo:[0,0,1] neg_hi:[0,0,1]
	v_pk_fma_f32 v[102:103], v[110:111], v[132:133], v[102:103]
	v_cvt_pk_bf16_f32 v97, v134, v135
	v_and_b32_e32 v108, 0xffff0000, v160
	v_cvt_pk_bf16_f32 v101, v102, v103
	v_lshlrev_b32_e32 v102, 16, v160
	v_lshlrev_b32_e32 v103, 16, v161
	v_and_b32_e32 v109, 0xffff0000, v161
	v_pk_mul_f32 v[110:111], v[98:99], v[108:109]
	v_pk_mul_f32 v[98:99], v[98:99], v[102:103]
	v_pk_fma_f32 v[110:111], v[104:105], v[102:103], v[110:111] neg_lo:[0,0,1] neg_hi:[0,0,1]
	v_pk_fma_f32 v[102:103], v[104:105], v[108:109], v[98:99]
	v_and_b32_e32 v108, 0xffff0000, v162
	v_and_b32_e32 v109, 0xffff0000, v163
	v_cvt_pk_bf16_f32 v98, v110, v111
	v_lshlrev_b32_e32 v104, 16, v162
	v_lshlrev_b32_e32 v105, 16, v163
	v_pk_mul_f32 v[110:111], v[130:131], v[108:109]
	v_cvt_pk_bf16_f32 v102, v102, v103
	s_nop 0
	v_pk_fma_f32 v[110:111], v[106:107], v[104:105], v[110:111] neg_lo:[0,0,1] neg_hi:[0,0,1]
	v_pk_mul_f32 v[104:105], v[130:131], v[104:105]
	v_cvt_pk_bf16_f32 v99, v110, v111
	s_nop 0
	v_pk_fma_f32 v[104:105], v[106:107], v[108:109], v[104:105]
	s_nop 0
	v_cvt_pk_bf16_f32 v103, v104, v105
	v_lshlrev_b64 v[104:105], s8, v[128:129]
	v_lshl_add_u64 v[104:105], v[104:105], 1, v[176:177]
	global_store_dwordx4 v[104:105], v[96:99], off
	global_store_dwordx4 v[104:105], v[100:103], off offset:128
	s_nop 0
	v_pk_fma_f32 v[98:99], v[82:83], s[56:57], v[114:115] op_sel_hi:[1,0,1]
	s_waitcnt vmcnt(14)
;     __device__ __forceinline__ void operator()(const pg8::f32x4 (&acc)[2][2][4][2], const pg8::Unit& u, int wr, int wc, int fr_, int fq_) const {
;     ...
;             for (int ai = 0; ai < 2; ++ai) {
;                 u32x4 rc[4][2];
; #pragma unroll
;                 for (int m = 0; m < 4; ++m) { const int pos = (row0 + ai * HALF + m * 16) & (SEQ - 1);
;                     const u32x4* rp = rope + ((size_t)pos * 64 + dlo) / 4;
;                     rc[m][0] = rp[0]; rc[m][1] = rp[1]; }
; #pragma unroll
;                 for (int m = 0; m < 4; ++m) {
;                     const int row = row0 + ai * HALF + m * 16;
;                     const u32x4 ca = rc[m][0], cb = rc[m][1];
;                     const f32x4 t1a = acc[ai][0][m][0] * ascale + bv[0][0], t1b = acc[ai][0][m][1] * ascale + bv[0][1];
;                     const f32x4 t2a = acc[ai][1][m][0] * ascale + bv[1][0], t2b = acc[ai][1][m][1] * ascale + bv[1][1];
;                     typedef float f2r __attribute__((ext_vector_type(2)));
;                     u32x4 w1, w2;
;     ...
;                     ROT2(t1a, t2a, ca, 0, w1.x, w2.x) ROT2(t1a, t2a, ca, 1, w1.y, w2.y) ROT2(t1b, t2b, cb, 0, w1.z, w2.z) ROT2(t1b, t2b, cb, 1, w1.w, w2.w)
;     ...
;                     bf16_t* rowp = dst + (size_t)row * pitch + head * HD + dlo;
;                     __builtin_nontemporal_store(w1, (u32x4*)(rowp)); __builtin_nontemporal_store(w2, (u32x4*)(rowp + 64));
	v_and_b32_e32 v100, 0xffff0000, v156
	v_and_b32_e32 v101, 0xffff0000, v157
	v_pk_fma_f32 v[82:83], v[80:81], s[56:57], v[112:113] op_sel_hi:[1,0,1]
	v_lshlrev_b32_e32 v80, 16, v156
	v_lshlrev_b32_e32 v81, 16, v157
	v_pk_mul_f32 v[102:103], v[84:85], v[100:101]
	v_add_u32_e32 v96, 32, v174
	v_pk_fma_f32 v[102:103], v[92:93], v[80:81], v[102:103] neg_lo:[0,0,1] neg_hi:[0,0,1]
	v_pk_mul_f32 v[80:81], v[84:85], v[80:81]
	v_ashrrev_i32_e32 v97, 31, v96
	v_pk_fma_f32 v[84:85], v[92:93], v[100:101], v[80:81]
	v_lshlrev_b32_e32 v92, 16, v158
	v_lshlrev_b32_e32 v93, 16, v159
	v_and_b32_e32 v100, 0xffff0000, v158
	v_and_b32_e32 v101, 0xffff0000, v159
	v_cvt_pk_bf16_f32 v80, v102, v103
	v_pk_mul_f32 v[102:103], v[86:87], v[100:101]
	v_pk_mul_f32 v[86:87], v[86:87], v[92:93]
	v_cvt_pk_bf16_f32 v84, v84, v85
	v_pk_fma_f32 v[102:103], v[94:95], v[92:93], v[102:103] neg_lo:[0,0,1] neg_hi:[0,0,1]
	v_pk_fma_f32 v[86:87], v[94:95], v[100:101], v[86:87]
	v_cvt_pk_bf16_f32 v81, v102, v103
	v_and_b32_e32 v92, 0xffff0000, v152
	v_cvt_pk_bf16_f32 v85, v86, v87
	v_lshlrev_b32_e32 v86, 16, v152
	v_lshlrev_b32_e32 v87, 16, v153
	v_and_b32_e32 v93, 0xffff0000, v153
	v_pk_mul_f32 v[94:95], v[82:83], v[92:93]
	v_pk_mul_f32 v[82:83], v[82:83], v[86:87]
	v_pk_fma_f32 v[94:95], v[88:89], v[86:87], v[94:95] neg_lo:[0,0,1] neg_hi:[0,0,1]
	v_pk_fma_f32 v[86:87], v[88:89], v[92:93], v[82:83]
	v_and_b32_e32 v92, 0xffff0000, v154
	v_and_b32_e32 v93, 0xffff0000, v155
	v_cvt_pk_bf16_f32 v82, v94, v95
	v_lshlrev_b32_e32 v88, 16, v154
	v_lshlrev_b32_e32 v89, 16, v155
	v_pk_mul_f32 v[94:95], v[98:99], v[92:93]
	v_cvt_pk_bf16_f32 v86, v86, v87
	s_nop 0
	v_pk_fma_f32 v[94:95], v[90:91], v[88:89], v[94:95] neg_lo:[0,0,1] neg_hi:[0,0,1]
	v_pk_mul_f32 v[88:89], v[98:99], v[88:89]
	v_cvt_pk_bf16_f32 v83, v94, v95
	v_pk_fma_f32 v[98:99], v[50:51], s[56:57], v[114:115] op_sel_hi:[1,0,1]
	v_pk_fma_f32 v[88:89], v[90:91], v[92:93], v[88:89]
	v_pk_fma_f32 v[50:51], v[48:49], s[56:57], v[112:113] op_sel_hi:[1,0,1]
	v_cvt_pk_bf16_f32 v87, v88, v89
	v_lshlrev_b64 v[88:89], s8, v[96:97]
	v_lshl_add_u64 v[88:89], v[88:89], 1, v[176:177]
	global_store_dwordx4 v[88:89], v[80:83], off
	global_store_dwordx4 v[88:89], v[84:87], off offset:128
	v_add_u32_e32 v96, 0x80, v174
	v_pk_fma_f32 v[82:83], v[66:67], s[56:57], v[114:115] op_sel_hi:[1,0,1]
	s_waitcnt vmcnt(14)
	v_and_b32_e32 v84, 0xffff0000, v148
	v_and_b32_e32 v85, 0xffff0000, v149
	v_pk_fma_f32 v[66:67], v[64:65], s[56:57], v[112:113] op_sel_hi:[1,0,1]
	v_lshlrev_b32_e32 v64, 16, v148
	v_lshlrev_b32_e32 v65, 16, v149
	v_pk_mul_f32 v[86:87], v[68:69], v[84:85]
	v_add_u32_e32 v80, 48, v174
	v_pk_fma_f32 v[86:87], v[76:77], v[64:65], v[86:87] neg_lo:[0,0,1] neg_hi:[0,0,1]
	v_pk_mul_f32 v[64:65], v[68:69], v[64:65]
	v_ashrrev_i32_e32 v81, 31, v80
	v_pk_fma_f32 v[68:69], v[76:77], v[84:85], v[64:65]
	v_lshlrev_b32_e32 v76, 16, v150
	v_lshlrev_b32_e32 v77, 16, v151
	v_and_b32_e32 v84, 0xffff0000, v150
	v_and_b32_e32 v85, 0xffff0000, v151
	v_cvt_pk_bf16_f32 v64, v86, v87
	v_pk_mul_f32 v[86:87], v[70:71], v[84:85]
	v_pk_mul_f32 v[70:71], v[70:71], v[76:77]
	v_cvt_pk_bf16_f32 v68, v68, v69
	v_pk_fma_f32 v[86:87], v[78:79], v[76:77], v[86:87] neg_lo:[0,0,1] neg_hi:[0,0,1]
	v_pk_fma_f32 v[70:71], v[78:79], v[84:85], v[70:71]
	v_cvt_pk_bf16_f32 v65, v86, v87
	v_and_b32_e32 v76, 0xffff0000, v144
	v_cvt_pk_bf16_f32 v69, v70, v71
	v_lshlrev_b32_e32 v70, 16, v144
	v_lshlrev_b32_e32 v71, 16, v145
	v_and_b32_e32 v77, 0xffff0000, v145
	v_pk_mul_f32 v[78:79], v[66:67], v[76:77]
	v_pk_mul_f32 v[66:67], v[66:67], v[70:71]
	v_pk_fma_f32 v[78:79], v[72:73], v[70:71], v[78:79] neg_lo:[0,0,1] neg_hi:[0,0,1]
	v_pk_fma_f32 v[70:71], v[72:73], v[76:77], v[66:67]
	v_and_b32_e32 v76, 0xffff0000, v146
	v_and_b32_e32 v77, 0xffff0000, v147
	v_cvt_pk_bf16_f32 v66, v78, v79
	v_lshlrev_b32_e32 v72, 16, v146
	v_lshlrev_b32_e32 v73, 16, v147
	v_pk_mul_f32 v[78:79], v[82:83], v[76:77]
	v_cvt_pk_bf16_f32 v70, v70, v71
	v_ashrrev_i32_e32 v97, 31, v96
	v_pk_fma_f32 v[78:79], v[74:75], v[72:73], v[78:79] neg_lo:[0,0,1] neg_hi:[0,0,1]
	v_pk_mul_f32 v[72:73], v[82:83], v[72:73]
	v_cvt_pk_bf16_f32 v67, v78, v79
	s_nop 0
	v_pk_fma_f32 v[72:73], v[74:75], v[76:77], v[72:73]
	s_nop 0
	v_cvt_pk_bf16_f32 v71, v72, v73
	v_lshlrev_b64 v[72:73], s8, v[80:81]
	v_lshl_add_u64 v[72:73], v[72:73], 1, v[176:177]
	global_store_dwordx4 v[72:73], v[64:67], off
	global_store_dwordx4 v[72:73], v[68:71], off offset:128
	s_nop 0
	v_add_u32_e32 v64, 0x2000, v188
	v_and_b32_e32 v172, 0xfffc0, v64
	v_lshl_add_u64 v[64:65], v[172:173], 0, v[178:179]
	v_lshl_add_u64 v[64:65], v[64:65], 2, s[46:47]
	s_waitcnt vmcnt(8)
;     __device__ __forceinline__ void operator()(const pg8::f32x4 (&acc)[2][2][4][2], const pg8::Unit& u, int wr, int wc, int fr_, int fq_) const {
;     ...
;                 for (int m = 0; m < 4; ++m) { const int pos = (row0 + ai * HALF + m * 16) & (SEQ - 1);
;                     const u32x4* rp = rope + ((size_t)pos * 64 + dlo) / 4;
;                     rc[m][0] = rp[0]; rc[m][1] = rp[1]; }
; #pragma unroll
;                 for (int m = 0; m < 4; ++m) {
;                     const int row = row0 + ai * HALF + m * 16;
;                     const u32x4 ca = rc[m][0], cb = rc[m][1];
;                     const f32x4 t1a = acc[ai][0][m][0] * ascale + bv[0][0], t1b = acc[ai][0][m][1] * ascale + bv[0][1];
;                     const f32x4 t2a = acc[ai][1][m][0] * ascale + bv[1][0], t2b = acc[ai][1][m][1] * ascale + bv[1][1];
;                     typedef float f2r __attribute__((ext_vector_type(2)));
;                     u32x4 w1, w2;
;     ...
;                     ROT2(t1a, t2a, ca, 0, w1.x, w2.x) ROT2(t1a, t2a, ca, 1, w1.y, w2.y) ROT2(t1b, t2b, cb, 0, w1.z, w2.z) ROT2(t1b, t2b, cb, 1, w1.w, w2.w)
;     ...
;                     bf16_t* rowp = dst + (size_t)row * pitch + head * HD + dlo;
;                     __builtin_nontemporal_store(w1, (u32x4*)(rowp)); __builtin_nontemporal_store(w2, (u32x4*)(rowp + 64));
	v_mov_b64_e32 v[80:81], v[200:201]
	v_mov_b64_e32 v[82:83], v[202:203]
	v_mov_b64_e32 v[84:85], v[204:205]
	v_mov_b64_e32 v[86:87], v[206:207]
	v_add_u32_e32 v64, 0x2400, v188
	v_and_b32_e32 v172, 0xfffc0, v64
	v_lshl_add_u64 v[64:65], v[172:173], 0, v[178:179]
	v_lshl_add_u64 v[64:65], v[64:65], 2, s[46:47]
	v_mov_b64_e32 v[88:89], v[208:209]
	v_mov_b64_e32 v[90:91], v[210:211]
	v_mov_b64_e32 v[92:93], v[212:213]
	v_mov_b64_e32 v[94:95], v[214:215]
	v_add_u32_e32 v64, 0x2800, v188
	v_and_b32_e32 v172, 0xfffc0, v64
	v_lshl_add_u64 v[64:65], v[172:173], 0, v[178:179]
	v_lshl_add_u64 v[64:65], v[64:65], 2, s[46:47]
	v_mov_b64_e32 v[72:73], v[216:217]
	v_mov_b64_e32 v[74:75], v[218:219]
	v_mov_b64_e32 v[76:77], v[220:221]
	v_mov_b64_e32 v[78:79], v[222:223]
	v_add_u32_e32 v64, 0x2c00, v188
	v_and_b32_e32 v172, 0xfffc0, v64
	v_lshl_add_u64 v[64:65], v[172:173], 0, v[178:179]
	v_lshl_add_u64 v[68:69], v[64:65], 2, s[46:47]
	v_mov_b64_e32 v[64:65], v[224:225]
	v_mov_b64_e32 v[66:67], v[226:227]
	s_nop 0
	v_mov_b64_e32 v[68:69], v[228:229]
	v_mov_b64_e32 v[70:71], v[230:231]
	v_mov_b64_e32 v[178:179], v[198:199]
	s_nop 0
	v_lshlrev_b32_e32 v48, 16, v84
	v_lshlrev_b32_e32 v49, 16, v85
	v_and_b32_e32 v84, 0xffff0000, v84
	v_and_b32_e32 v85, 0xffff0000, v85
	v_pk_mul_f32 v[100:101], v[52:53], v[84:85]
	s_nop 0
	v_pk_fma_f32 v[100:101], v[60:61], v[48:49], v[100:101] neg_lo:[0,0,1] neg_hi:[0,0,1]
	v_pk_mul_f32 v[48:49], v[52:53], v[48:49]
	s_nop 0
	v_pk_fma_f32 v[52:53], v[60:61], v[84:85], v[48:49]
	v_lshlrev_b32_e32 v60, 16, v86
	v_lshlrev_b32_e32 v61, 16, v87
	v_and_b32_e32 v84, 0xffff0000, v86
	v_and_b32_e32 v85, 0xffff0000, v87
	v_pk_mul_f32 v[86:87], v[54:55], v[84:85]
	v_pk_mul_f32 v[54:55], v[54:55], v[60:61]
	v_cvt_pk_bf16_f32 v48, v100, v101
	v_cvt_pk_bf16_f32 v52, v52, v53
	v_pk_fma_f32 v[86:87], v[62:63], v[60:61], v[86:87] neg_lo:[0,0,1] neg_hi:[0,0,1]
	v_pk_fma_f32 v[54:55], v[62:63], v[84:85], v[54:55]
	v_cvt_pk_bf16_f32 v49, v86, v87
	v_and_b32_e32 v60, 0xffff0000, v80
	v_cvt_pk_bf16_f32 v53, v54, v55
	v_lshlrev_b32_e32 v54, 16, v80
	v_lshlrev_b32_e32 v55, 16, v81
	v_and_b32_e32 v61, 0xffff0000, v81
	v_pk_mul_f32 v[62:63], v[50:51], v[60:61]
	v_pk_mul_f32 v[50:51], v[50:51], v[54:55]
	v_pk_fma_f32 v[62:63], v[56:57], v[54:55], v[62:63] neg_lo:[0,0,1] neg_hi:[0,0,1]
	v_pk_fma_f32 v[54:55], v[56:57], v[60:61], v[50:51]
	v_and_b32_e32 v60, 0xffff0000, v82
	v_and_b32_e32 v61, 0xffff0000, v83
	v_cvt_pk_bf16_f32 v50, v62, v63
	v_lshlrev_b32_e32 v56, 16, v82
	v_lshlrev_b32_e32 v57, 16, v83
	v_pk_mul_f32 v[62:63], v[98:99], v[60:61]
	v_cvt_pk_bf16_f32 v54, v54, v55
	s_nop 0
	v_pk_fma_f32 v[62:63], v[58:59], v[56:57], v[62:63] neg_lo:[0,0,1] neg_hi:[0,0,1]
	v_pk_mul_f32 v[56:57], v[98:99], v[56:57]
	v_cvt_pk_bf16_f32 v51, v62, v63
	s_nop 0
	v_pk_fma_f32 v[56:57], v[58:59], v[60:61], v[56:57]
	s_nop 0
	v_cvt_pk_bf16_f32 v55, v56, v57
	v_lshlrev_b64 v[56:57], s8, v[96:97]
	v_lshl_add_u64 v[56:57], v[56:57], 1, v[176:177]
	global_store_dwordx4 v[56:57], v[48:51], off
	global_store_dwordx4 v[56:57], v[52:55], off offset:128
	s_nop 0
	v_pk_fma_f32 v[50:51], v[34:35], s[56:57], v[114:115] op_sel_hi:[1,0,1]
	s_nop 0
	v_and_b32_e32 v52, 0xffff0000, v92
	v_and_b32_e32 v53, 0xffff0000, v93
	v_pk_fma_f32 v[34:35], v[32:33], s[56:57], v[112:113] op_sel_hi:[1,0,1]
	v_lshlrev_b32_e32 v32, 16, v92
	v_lshlrev_b32_e32 v33, 16, v93
	v_pk_mul_f32 v[54:55], v[36:37], v[52:53]
	v_add_u32_e32 v48, 0x90, v174
	v_pk_fma_f32 v[54:55], v[44:45], v[32:33], v[54:55] neg_lo:[0,0,1] neg_hi:[0,0,1]
	v_pk_mul_f32 v[32:33], v[36:37], v[32:33]
	v_ashrrev_i32_e32 v49, 31, v48
	v_pk_fma_f32 v[36:37], v[44:45], v[52:53], v[32:33]
	v_lshlrev_b32_e32 v44, 16, v94
	v_lshlrev_b32_e32 v45, 16, v95
	v_and_b32_e32 v52, 0xffff0000, v94
	v_and_b32_e32 v53, 0xffff0000, v95
	v_cvt_pk_bf16_f32 v32, v54, v55
	v_pk_mul_f32 v[54:55], v[38:39], v[52:53]
	v_pk_mul_f32 v[38:39], v[38:39], v[44:45]
	v_cvt_pk_bf16_f32 v36, v36, v37
	v_pk_fma_f32 v[54:55], v[46:47], v[44:45], v[54:55] neg_lo:[0,0,1] neg_hi:[0,0,1]
	v_pk_fma_f32 v[38:39], v[46:47], v[52:53], v[38:39]
	v_cvt_pk_bf16_f32 v33, v54, v55
	v_and_b32_e32 v44, 0xffff0000, v88
	v_cvt_pk_bf16_f32 v37, v38, v39
	v_lshlrev_b32_e32 v38, 16, v88
	v_lshlrev_b32_e32 v39, 16, v89
	v_and_b32_e32 v45, 0xffff0000, v89
	v_pk_mul_f32 v[46:47], v[34:35], v[44:45]
	v_pk_mul_f32 v[34:35], v[34:35], v[38:39]
	v_pk_fma_f32 v[46:47], v[40:41], v[38:39], v[46:47] neg_lo:[0,0,1] neg_hi:[0,0,1]
	v_pk_fma_f32 v[38:39], v[40:41], v[44:45], v[34:35]
	v_and_b32_e32 v44, 0xffff0000, v90
	v_and_b32_e32 v45, 0xffff0000, v91
	v_cvt_pk_bf16_f32 v34, v46, v47
	v_lshlrev_b32_e32 v40, 16, v90
	v_lshlrev_b32_e32 v41, 16, v91
	v_pk_mul_f32 v[46:47], v[50:51], v[44:45]
	v_cvt_pk_bf16_f32 v38, v38, v39
;     __device__ __forceinline__ void operator()(const pg8::f32x4 (&acc)[2][2][4][2], const pg8::Unit& u, int wr, int wc, int fr_, int fq_) const {
;     ...
;                 for (int m = 0; m < 4; ++m) {
;                     const int row = row0 + ai * HALF + m * 16;
;                     const u32x4 ca = rc[m][0], cb = rc[m][1];
;                     const f32x4 t1a = acc[ai][0][m][0] * ascale + bv[0][0], t1b = acc[ai][0][m][1] * ascale + bv[0][1];
;                     const f32x4 t2a = acc[ai][1][m][0] * ascale + bv[1][0], t2b = acc[ai][1][m][1] * ascale + bv[1][1];
;                     typedef float f2r __attribute__((ext_vector_type(2)));
;                     u32x4 w1, w2;
;     ...
;                     ROT2(t1a, t2a, ca, 0, w1.x, w2.x) ROT2(t1a, t2a, ca, 1, w1.y, w2.y) ROT2(t1b, t2b, cb, 0, w1.z, w2.z) ROT2(t1b, t2b, cb, 1, w1.w, w2.w)
;     ...
;                     bf16_t* rowp = dst + (size_t)row * pitch + head * HD + dlo;
;                     __builtin_nontemporal_store(w1, (u32x4*)(rowp)); __builtin_nontemporal_store(w2, (u32x4*)(rowp + 64));
	s_nop 0
	v_pk_fma_f32 v[46:47], v[42:43], v[40:41], v[46:47] neg_lo:[0,0,1] neg_hi:[0,0,1]
	v_pk_mul_f32 v[40:41], v[50:51], v[40:41]
	v_cvt_pk_bf16_f32 v35, v46, v47
	s_nop 0
	v_pk_fma_f32 v[40:41], v[42:43], v[44:45], v[40:41]
	s_nop 0
	v_cvt_pk_bf16_f32 v39, v40, v41
	v_lshlrev_b64 v[40:41], s8, v[48:49]
	v_lshl_add_u64 v[40:41], v[40:41], 1, v[176:177]
	global_store_dwordx4 v[40:41], v[32:35], off
	global_store_dwordx4 v[40:41], v[36:39], off offset:128
	s_nop 0
	v_pk_fma_f32 v[34:35], v[18:19], s[56:57], v[114:115] op_sel_hi:[1,0,1]
	s_nop 0
	v_and_b32_e32 v36, 0xffff0000, v76
	v_and_b32_e32 v37, 0xffff0000, v77
	v_pk_fma_f32 v[18:19], v[16:17], s[56:57], v[112:113] op_sel_hi:[1,0,1]
	v_lshlrev_b32_e32 v16, 16, v76
	v_lshlrev_b32_e32 v17, 16, v77
	v_pk_mul_f32 v[38:39], v[20:21], v[36:37]
	v_add_u32_e32 v32, 0xa0, v174
	v_pk_fma_f32 v[38:39], v[28:29], v[16:17], v[38:39] neg_lo:[0,0,1] neg_hi:[0,0,1]
	v_pk_mul_f32 v[16:17], v[20:21], v[16:17]
	v_ashrrev_i32_e32 v33, 31, v32
	v_pk_fma_f32 v[20:21], v[28:29], v[36:37], v[16:17]
	v_lshlrev_b32_e32 v28, 16, v78
	v_lshlrev_b32_e32 v29, 16, v79
	v_and_b32_e32 v36, 0xffff0000, v78
	v_and_b32_e32 v37, 0xffff0000, v79
	v_cvt_pk_bf16_f32 v16, v38, v39
	v_pk_mul_f32 v[38:39], v[22:23], v[36:37]
	v_pk_mul_f32 v[22:23], v[22:23], v[28:29]
	v_cvt_pk_bf16_f32 v20, v20, v21
	v_pk_fma_f32 v[38:39], v[30:31], v[28:29], v[38:39] neg_lo:[0,0,1] neg_hi:[0,0,1]
	v_pk_fma_f32 v[22:23], v[30:31], v[36:37], v[22:23]
	v_cvt_pk_bf16_f32 v17, v38, v39
	v_and_b32_e32 v28, 0xffff0000, v72
	v_cvt_pk_bf16_f32 v21, v22, v23
	v_lshlrev_b32_e32 v22, 16, v72
	v_lshlrev_b32_e32 v23, 16, v73
	v_and_b32_e32 v29, 0xffff0000, v73
	v_pk_mul_f32 v[30:31], v[18:19], v[28:29]
	v_pk_mul_f32 v[18:19], v[18:19], v[22:23]
	v_pk_fma_f32 v[30:31], v[24:25], v[22:23], v[30:31] neg_lo:[0,0,1] neg_hi:[0,0,1]
	v_pk_fma_f32 v[22:23], v[24:25], v[28:29], v[18:19]
	v_and_b32_e32 v28, 0xffff0000, v74
	v_and_b32_e32 v29, 0xffff0000, v75
	v_cvt_pk_bf16_f32 v18, v30, v31
	v_lshlrev_b32_e32 v24, 16, v74
	v_lshlrev_b32_e32 v25, 16, v75
	v_pk_mul_f32 v[30:31], v[34:35], v[28:29]
	v_cvt_pk_bf16_f32 v22, v22, v23
	s_nop 0
	v_pk_fma_f32 v[30:31], v[26:27], v[24:25], v[30:31] neg_lo:[0,0,1] neg_hi:[0,0,1]
	v_pk_mul_f32 v[24:25], v[34:35], v[24:25]
	v_cvt_pk_bf16_f32 v19, v30, v31
	s_nop 0
	v_pk_fma_f32 v[24:25], v[26:27], v[28:29], v[24:25]
	s_nop 0
	v_cvt_pk_bf16_f32 v23, v24, v25
	v_lshlrev_b64 v[24:25], s8, v[32:33]
	v_lshl_add_u64 v[24:25], v[24:25], 1, v[176:177]
	global_store_dwordx4 v[24:25], v[16:19], off
	global_store_dwordx4 v[24:25], v[20:23], off offset:128
	s_nop 0
	v_pk_fma_f32 v[18:19], v[2:3], s[56:57], v[114:115] op_sel_hi:[1,0,1]
	s_nop 0
	v_and_b32_e32 v20, 0xffff0000, v68
	v_and_b32_e32 v21, 0xffff0000, v69
	v_pk_fma_f32 v[2:3], v[0:1], s[56:57], v[112:113] op_sel_hi:[1,0,1]
	v_lshlrev_b32_e32 v0, 16, v68
	v_lshlrev_b32_e32 v1, 16, v69
	v_pk_mul_f32 v[22:23], v[4:5], v[20:21]
	v_add_u32_e32 v16, 0xb0, v174
	v_pk_fma_f32 v[22:23], v[12:13], v[0:1], v[22:23] neg_lo:[0,0,1] neg_hi:[0,0,1]
	v_pk_mul_f32 v[0:1], v[4:5], v[0:1]
	v_ashrrev_i32_e32 v17, 31, v16
	v_pk_fma_f32 v[4:5], v[12:13], v[20:21], v[0:1]
	v_lshlrev_b32_e32 v12, 16, v70
	v_lshlrev_b32_e32 v13, 16, v71
	v_and_b32_e32 v20, 0xffff0000, v70
	v_and_b32_e32 v21, 0xffff0000, v71
	v_cvt_pk_bf16_f32 v0, v22, v23
	v_pk_mul_f32 v[22:23], v[6:7], v[20:21]
	v_pk_mul_f32 v[6:7], v[6:7], v[12:13]
	v_cvt_pk_bf16_f32 v4, v4, v5
	v_pk_fma_f32 v[22:23], v[14:15], v[12:13], v[22:23] neg_lo:[0,0,1] neg_hi:[0,0,1]
	v_pk_fma_f32 v[6:7], v[14:15], v[20:21], v[6:7]
	v_cvt_pk_bf16_f32 v1, v22, v23
	v_and_b32_e32 v12, 0xffff0000, v64
	v_cvt_pk_bf16_f32 v5, v6, v7
	v_lshlrev_b32_e32 v6, 16, v64
	v_lshlrev_b32_e32 v7, 16, v65
	v_and_b32_e32 v13, 0xffff0000, v65
	v_pk_mul_f32 v[14:15], v[2:3], v[12:13]
	v_pk_mul_f32 v[2:3], v[2:3], v[6:7]
	v_pk_fma_f32 v[14:15], v[8:9], v[6:7], v[14:15] neg_lo:[0,0,1] neg_hi:[0,0,1]
	v_pk_fma_f32 v[6:7], v[8:9], v[12:13], v[2:3]
	v_and_b32_e32 v12, 0xffff0000, v66
	v_and_b32_e32 v13, 0xffff0000, v67
	v_cvt_pk_bf16_f32 v2, v14, v15
	v_lshlrev_b32_e32 v8, 16, v66
	v_lshlrev_b32_e32 v9, 16, v67
	v_pk_mul_f32 v[14:15], v[18:19], v[12:13]
	v_cvt_pk_bf16_f32 v6, v6, v7
	s_nop 0
	v_pk_fma_f32 v[14:15], v[10:11], v[8:9], v[14:15] neg_lo:[0,0,1] neg_hi:[0,0,1]
	v_pk_mul_f32 v[8:9], v[18:19], v[8:9]
	v_cvt_pk_bf16_f32 v3, v14, v15
	s_nop 0
	v_pk_fma_f32 v[8:9], v[10:11], v[12:13], v[8:9]
	s_nop 0
	v_cvt_pk_bf16_f32 v7, v8, v9
	v_lshlrev_b64 v[8:9], s8, v[16:17]
	v_lshl_add_u64 v[8:9], v[8:9], 1, v[176:177]
	global_store_dwordx4 v[8:9], v[0:3], off
	global_store_dwordx4 v[8:9], v[4:7], off offset:128
	s_andn2_b64 vcc, exec, s[0:1]
	s_mov_b64 s[0:1], -1
	s_cbranch_vccnz .LBB0_407
	s_branch .LBB0_441
